# states phase item top: X^T fragment and W row loads issued together with the Bm tile loads (one exposed memory latency instead of two)
# speedup vs baseline: 1.0070x; 1.0070x over previous
.LBB0_1978:
	s_ashr_i32 s6, s16, 3
	s_and_b32 s7, s16, 7
	s_lshl_b32 s17, s6, 7
	s_lshl_b32 s4, s7, 8
	v_readlane_b32 s12, v252, 45
	v_readlane_b32 s13, v252, 46
	s_add_u32 s12, s12, s4
	s_addc_u32 s13, s13, 0
	s_lshl_b32 s4, s17, 11
	s_add_u32 s12, s12, s4
	s_addc_u32 s13, s13, 0
	v_lshl_add_u32 v95, v234, 11, v72
	global_load_dwordx4 v[96:99], v95, s[12:13]
	s_add_u32 s12, s12, 0x8000
	s_addc_u32 s13, s13, 0
	global_load_dwordx4 v[100:103], v95, s[12:13]
	s_add_u32 s12, s12, 0x8000
	s_addc_u32 s13, s13, 0
	global_load_dwordx4 v[104:107], v95, s[12:13]
	s_add_u32 s12, s12, 0x8000
	s_addc_u32 s13, s13, 0
	global_load_dwordx4 v[108:111], v95, s[12:13]
	s_add_u32 s12, s12, 0x8000
	s_addc_u32 s13, s13, 0
	global_load_dwordx4 v[112:115], v95, s[12:13]
	s_add_u32 s12, s12, 0x8000
	s_addc_u32 s13, s13, 0
	global_load_dwordx4 v[116:119], v95, s[12:13]
	s_add_u32 s12, s12, 0x8000
	s_addc_u32 s13, s13, 0
	global_load_dwordx4 v[120:123], v95, s[12:13]
	s_add_u32 s12, s12, 0x8000
	s_addc_u32 s13, s13, 0
	global_load_dwordx4 v[124:127], v95, s[12:13]
	v_ashrrev_i32_e32 v0, 6, v65
	v_lshl_add_u32 v74, s7, 2, v0
	s_ashr_i32 s7, s6, 31
	v_lshlrev_b32_e32 v0, 6, v74
	s_lshl_b64 s[4:5], s[6:7], 11
	v_ashrrev_i32_e32 v1, 31, v0
	v_lshl_add_u64 v[0:1], s[4:5], 0, v[0:1]
	v_or_b32_e32 v0, v0, v64
	v_lshlrev_b64 v[0:1], 8, v[0:1]
	v_lshl_add_u64 v[0:1], v[66:67], 0, v[0:1]
	s_movk_i32 s11, 0x2000
	v_add_co_u32_e64 v2, s[4:5], s11, v0
	s_waitcnt lgkmcnt(0)
	s_nop 0
	v_addc_co_u32_e64 v3, s[4:5], 0, v1, s[4:5]
	s_load_dwordx2 s[100:101], s[60:61], 0xe8
	v_readfirstlane_b32 s4, v74
	v_lshlrev_b32_e32 v84, 3, v221
	s_lshl_b32 s5, s6, 15
	s_waitcnt lgkmcnt(0)
	s_add_u32 s100, s100, s5
	s_addc_u32 s101, s101, 0
	s_lshl_b32 s4, s4, 9
	s_add_u32 s100, s100, s4
	s_addc_u32 s101, s101, 0
	s_add_u32 s100, s100, 0xd08000
	s_addc_u32 s101, s101, 0
	global_load_dwordx2 v[80:81], v84, s[100:101]
	s_add_u32 s100, s100, 0x4000
	s_addc_u32 s101, s101, 0
	global_load_dwordx2 v[82:83], v84, s[100:101]
	global_load_dwordx4 v[24:27], v[0:1], off
	global_load_dwordx4 v[28:31], v[0:1], off offset:32
	global_load_dwordx4 v[32:35], v[0:1], off offset:64
	global_load_dwordx4 v[36:39], v[0:1], off offset:96
	global_load_dwordx4 v[40:43], v[2:3], off
	global_load_dwordx4 v[44:47], v[2:3], off offset:32
	global_load_dwordx4 v[48:51], v[2:3], off offset:64
	global_load_dwordx4 v[52:55], v[2:3], off offset:96
	global_load_dwordx4 v[56:59], v[0:1], off offset:128
	global_load_dwordx4 v[60:63], v[2:3], off offset:128
	global_load_dwordx4 v[20:23], v[0:1], off offset:160
	global_load_dwordx4 v[12:15], v[0:1], off offset:192
	global_load_dwordx4 v[4:7], v[0:1], off offset:224
	global_load_dwordx4 v[16:19], v[2:3], off offset:160
	global_load_dwordx4 v[8:11], v[2:3], off offset:192
	s_nop 0
	global_load_dwordx4 v[0:3], v[2:3], off offset:224
	s_barrier
	s_waitcnt vmcnt(25)
	ds_write_b16 v235, v96
	ds_write_b16_d16_hi v235, v96 offset:272
	ds_write_b16 v235, v97 offset:544
	ds_write_b16_d16_hi v235, v97 offset:816
	ds_write_b16 v235, v98 offset:1088
	ds_write_b16_d16_hi v235, v98 offset:1360
	ds_write_b16 v235, v99 offset:1632
	ds_write_b16_d16_hi v235, v99 offset:1904
	s_waitcnt vmcnt(24)
	ds_write_b16 v235, v100 offset:32
	ds_write_b16_d16_hi v235, v100 offset:304
	ds_write_b16 v235, v101 offset:576
	ds_write_b16_d16_hi v235, v101 offset:848
	ds_write_b16 v235, v102 offset:1120
	ds_write_b16_d16_hi v235, v102 offset:1392
	ds_write_b16 v235, v103 offset:1664
	ds_write_b16_d16_hi v235, v103 offset:1936
	s_waitcnt vmcnt(23)
	ds_write_b16 v235, v104 offset:64
	ds_write_b16_d16_hi v235, v104 offset:336
	ds_write_b16 v235, v105 offset:608
	ds_write_b16_d16_hi v235, v105 offset:880
	ds_write_b16 v235, v106 offset:1152
	ds_write_b16_d16_hi v235, v106 offset:1424
	ds_write_b16 v235, v107 offset:1696
	ds_write_b16_d16_hi v235, v107 offset:1968
	s_waitcnt vmcnt(22)
	ds_write_b16 v235, v108 offset:96
	ds_write_b16_d16_hi v235, v108 offset:368
	ds_write_b16 v235, v109 offset:640
	ds_write_b16_d16_hi v235, v109 offset:912
	ds_write_b16 v235, v110 offset:1184
	ds_write_b16_d16_hi v235, v110 offset:1456
	ds_write_b16 v235, v111 offset:1728
	ds_write_b16_d16_hi v235, v111 offset:2000
	s_waitcnt vmcnt(21)
	ds_write_b16 v235, v112 offset:128
	ds_write_b16_d16_hi v235, v112 offset:400
	ds_write_b16 v235, v113 offset:672
	ds_write_b16_d16_hi v235, v113 offset:944
	ds_write_b16 v235, v114 offset:1216
	ds_write_b16_d16_hi v235, v114 offset:1488
	ds_write_b16 v235, v115 offset:1760
	ds_write_b16_d16_hi v235, v115 offset:2032
	s_waitcnt vmcnt(20)
	ds_write_b16 v235, v116 offset:160
	ds_write_b16_d16_hi v235, v116 offset:432
	ds_write_b16 v235, v117 offset:704
	ds_write_b16_d16_hi v235, v117 offset:976
	ds_write_b16 v235, v118 offset:1248
	ds_write_b16_d16_hi v235, v118 offset:1520
	ds_write_b16 v235, v119 offset:1792
	ds_write_b16_d16_hi v235, v119 offset:2064
	s_waitcnt vmcnt(19)
	ds_write_b16 v235, v120 offset:192
	ds_write_b16_d16_hi v235, v120 offset:464
	ds_write_b16 v235, v121 offset:736
	ds_write_b16_d16_hi v235, v121 offset:1008
	ds_write_b16 v235, v122 offset:1280
	ds_write_b16_d16_hi v235, v122 offset:1552
	ds_write_b16 v235, v123 offset:1824
	ds_write_b16_d16_hi v235, v123 offset:2096
	s_waitcnt vmcnt(18)
	ds_write_b16 v235, v124 offset:224
	ds_write_b16_d16_hi v235, v124 offset:496
	ds_write_b16 v235, v125 offset:768
	ds_write_b16_d16_hi v235, v125 offset:1040
	ds_write_b16 v235, v126 offset:1312
	ds_write_b16_d16_hi v235, v126 offset:1584
	ds_write_b16 v235, v127 offset:1856
	ds_write_b16_d16_hi v235, v127 offset:2128
	s_waitcnt lgkmcnt(0)
	s_barrier
	s_lshl_b64 s[4:5], s[6:7], 15
	s_lshl_b64 s[6:7], s[6:7], 6
	v_ashrrev_i32_e32 v75, 31, v74
	v_readlane_b32 s14, v252, 12
	s_mov_b32 s10, 0
	v_lshl_add_u64 v[76:77], v[68:69], 0, s[4:5]
	v_lshl_add_u64 v[78:79], s[6:7], 0, v[74:75]
	s_mov_b32 s6, 0
	s_movk_i32 s7, 0x3000
	s_movk_i32 s12, 0x1000
	v_readlane_b32 s15, v252, 13
	s_waitcnt vmcnt(16)
	ds_write_b64 v253, v[80:81]
	ds_write_b64 v253, v[82:83] offset:512
	s_waitcnt vmcnt(15)
	v_lshlrev_b32_e32 v80, 16, v24
	v_and_b32_e32 v81, 0xffff0000, v24
	v_lshlrev_b32_e32 v82, 16, v25
	v_and_b32_e32 v83, 0xffff0000, v25
	v_lshlrev_b32_e32 v84, 16, v26
	v_and_b32_e32 v85, 0xffff0000, v26
	v_lshlrev_b32_e32 v86, 16, v27
	v_and_b32_e32 v87, 0xffff0000, v27
	s_waitcnt vmcnt(14)
	v_lshlrev_b32_e32 v88, 16, v28
	v_and_b32_e32 v89, 0xffff0000, v28
	v_lshlrev_b32_e32 v90, 16, v29
	v_and_b32_e32 v91, 0xffff0000, v29
	v_lshlrev_b32_e32 v92, 16, v30
	v_and_b32_e32 v93, 0xffff0000, v30
	v_lshlrev_b32_e32 v94, 16, v31
	v_and_b32_e32 v95, 0xffff0000, v31
	s_waitcnt vmcnt(13)
	v_lshlrev_b32_e32 v96, 16, v32
	v_and_b32_e32 v97, 0xffff0000, v32
	v_lshlrev_b32_e32 v98, 16, v33
	v_and_b32_e32 v99, 0xffff0000, v33
	v_lshlrev_b32_e32 v100, 16, v34
	v_and_b32_e32 v101, 0xffff0000, v34
	v_lshlrev_b32_e32 v102, 16, v35
	v_and_b32_e32 v103, 0xffff0000, v35
	s_waitcnt vmcnt(12)
	v_lshlrev_b32_e32 v104, 16, v36
	v_and_b32_e32 v105, 0xffff0000, v36
	v_lshlrev_b32_e32 v106, 16, v37
	s_waitcnt vmcnt(11)
	v_lshlrev_b32_e32 v108, 16, v40
	v_and_b32_e32 v109, 0xffff0000, v40
	v_lshlrev_b32_e32 v110, 16, v41
	v_and_b32_e32 v111, 0xffff0000, v41
	v_lshlrev_b32_e32 v112, 16, v42
	v_and_b32_e32 v113, 0xffff0000, v42
	v_lshlrev_b32_e32 v114, 16, v43
	v_and_b32_e32 v115, 0xffff0000, v43
	s_waitcnt vmcnt(10)
	v_lshlrev_b32_e32 v116, 16, v44
	v_and_b32_e32 v117, 0xffff0000, v44
	v_lshlrev_b32_e32 v118, 16, v45
	v_and_b32_e32 v119, 0xffff0000, v45
	v_lshlrev_b32_e32 v120, 16, v46
	v_and_b32_e32 v121, 0xffff0000, v46
	v_lshlrev_b32_e32 v122, 16, v47
	v_and_b32_e32 v123, 0xffff0000, v47
	s_waitcnt vmcnt(9)
	v_lshlrev_b32_e32 v124, 16, v48
	v_and_b32_e32 v125, 0xffff0000, v48
	v_lshlrev_b32_e32 v126, 16, v49
	v_and_b32_e32 v127, 0xffff0000, v49
	v_lshlrev_b32_e32 v130, 16, v50
	v_and_b32_e32 v131, 0xffff0000, v50
	v_lshlrev_b32_e32 v132, 16, v51
	v_and_b32_e32 v133, 0xffff0000, v51
	v_and_b32_e32 v107, 0xffff0000, v37
	v_lshlrev_b32_e32 v134, 16, v38
	v_and_b32_e32 v135, 0xffff0000, v38
	v_lshlrev_b32_e32 v136, 16, v39
	v_and_b32_e32 v137, 0xffff0000, v39
	s_waitcnt vmcnt(8)
	v_lshlrev_b32_e32 v138, 16, v52
	v_and_b32_e32 v139, 0xffff0000, v52
	v_lshlrev_b32_e32 v140, 16, v53
	v_and_b32_e32 v141, 0xffff0000, v53
	v_lshlrev_b32_e32 v142, 16, v54
	v_and_b32_e32 v143, 0xffff0000, v54
	v_lshlrev_b32_e32 v144, 16, v55
	v_and_b32_e32 v145, 0xffff0000, v55
	s_waitcnt vmcnt(7)
	v_lshlrev_b32_e32 v146, 16, v56
	v_and_b32_e32 v147, 0xffff0000, v56
	v_lshlrev_b32_e32 v148, 16, v57
	v_and_b32_e32 v149, 0xffff0000, v57
	v_lshlrev_b32_e32 v150, 16, v58
	v_and_b32_e32 v151, 0xffff0000, v58
	v_lshlrev_b32_e32 v152, 16, v59
	v_and_b32_e32 v153, 0xffff0000, v59
	s_waitcnt vmcnt(6)
	v_lshlrev_b32_e32 v154, 16, v60
	v_and_b32_e32 v155, 0xffff0000, v60
	v_lshlrev_b32_e32 v156, 16, v61
	v_and_b32_e32 v157, 0xffff0000, v61
	v_lshlrev_b32_e32 v158, 16, v62
	v_and_b32_e32 v159, 0xffff0000, v62
	v_lshlrev_b32_e32 v160, 16, v63
	v_and_b32_e32 v161, 0xffff0000, v63
	s_waitcnt vmcnt(5)
	v_lshlrev_b32_e32 v168, 16, v20
	v_and_b32_e32 v169, 0xffff0000, v20
	v_lshlrev_b32_e32 v170, 16, v21
	v_and_b32_e32 v171, 0xffff0000, v21
	v_lshlrev_b32_e32 v172, 16, v22
	v_and_b32_e32 v173, 0xffff0000, v22
	v_lshlrev_b32_e32 v174, 16, v23
	v_and_b32_e32 v175, 0xffff0000, v23
	s_waitcnt vmcnt(2)
	v_lshlrev_b32_e32 v176, 16, v16
	v_and_b32_e32 v177, 0xffff0000, v16
	v_lshlrev_b32_e32 v178, 16, v17
	v_and_b32_e32 v179, 0xffff0000, v17
	v_lshlrev_b32_e32 v180, 16, v18
	v_and_b32_e32 v181, 0xffff0000, v18
	v_lshlrev_b32_e32 v182, 16, v19
	v_and_b32_e32 v183, 0xffff0000, v19
	v_lshlrev_b32_e32 v184, 16, v12
	v_and_b32_e32 v185, 0xffff0000, v12
	v_lshlrev_b32_e32 v186, 16, v13
	v_and_b32_e32 v187, 0xffff0000, v13
	v_lshlrev_b32_e32 v188, 16, v14
	v_and_b32_e32 v189, 0xffff0000, v14
	v_lshlrev_b32_e32 v190, 16, v15
	v_and_b32_e32 v191, 0xffff0000, v15
	s_waitcnt vmcnt(1)
	v_lshlrev_b32_e32 v192, 16, v8
	v_and_b32_e32 v193, 0xffff0000, v8
	v_lshlrev_b32_e32 v194, 16, v9
	v_and_b32_e32 v195, 0xffff0000, v9
	v_lshlrev_b32_e32 v196, 16, v10
	v_and_b32_e32 v197, 0xffff0000, v10
	v_lshlrev_b32_e32 v198, 16, v11
	v_and_b32_e32 v199, 0xffff0000, v11
	v_lshlrev_b32_e32 v200, 16, v4
	v_and_b32_e32 v201, 0xffff0000, v4
	v_lshlrev_b32_e32 v202, 16, v5
	v_and_b32_e32 v203, 0xffff0000, v5
	v_lshlrev_b32_e32 v204, 16, v6
	v_and_b32_e32 v205, 0xffff0000, v6
	v_lshlrev_b32_e32 v206, 16, v7
	v_and_b32_e32 v207, 0xffff0000, v7
	s_waitcnt vmcnt(0)
	v_lshlrev_b32_e32 v208, 16, v0
	v_and_b32_e32 v209, 0xffff0000, v0
	v_lshlrev_b32_e32 v210, 16, v1
	v_and_b32_e32 v211, 0xffff0000, v1
	v_lshlrev_b32_e32 v212, 16, v2
	v_and_b32_e32 v213, 0xffff0000, v2
	v_lshlrev_b32_e32 v214, 16, v3
	v_and_b32_e32 v215, 0xffff0000, v3
